# seam flattening: XCD leaders poll the arrival counter TOP directly; last leader's TOPGEN add removed
# speedup vs baseline: 1.0011x; 1.0011x over previous
.LBB0_93:
	s_andn2_saveexec_b64 s[0:1], s[0:1]
	s_cbranch_execz .LBB0_109
	v_mov_b32_e32 v1, s38
	v_add_co_u32_e32 v2, vcc, 0x3000, v1
	v_mov_b32_e32 v1, s39
	buffer_wbl2 sc1
	s_waitcnt vmcnt(0)
	buffer_inv sc1
	v_addc_co_u32_e32 v3, vcc, 0, v1, vcc
	v_mov_b32_e32 v1, 1
	flat_atomic_add v1, v[2:3], v1 offset:1024 sc0
	v_cvt_f32_u32_e32 v2, v0
	v_sub_u32_e32 v3, 0, v0
	s_add_u32 s0, s38, 0x3500
	s_addc_u32 s1, s39, 0
	s_add_u32 s98, s38, 0x3400
	s_addc_u32 s99, s39, 0
	v_rcp_iflag_f32_e32 v2, v2
	s_mov_b64 s[6:7], 0
	v_mul_f32_e32 v2, 0x4f7ffffe, v2
	v_cvt_u32_f32_e32 v2, v2
	v_mul_lo_u32 v3, v3, v2
	v_mul_hi_u32 v3, v2, v3
	v_add_u32_e32 v2, v2, v3
	s_waitcnt vmcnt(0) lgkmcnt(0)
	v_mul_hi_u32 v2, v1, v2
	v_mul_lo_u32 v4, v2, v0
	v_add_u32_e32 v3, 1, v1
	v_sub_u32_e32 v1, v1, v4
	v_add_u32_e32 v5, 1, v2
	v_cmp_ge_u32_e32 vcc, v1, v0
	v_sub_u32_e32 v4, v1, v0
	s_nop 0
	v_cndmask_b32_e32 v2, v2, v5, vcc
	v_cndmask_b32_e32 v1, v1, v4, vcc
	v_add_u32_e32 v4, 1, v2
	v_cmp_ge_u32_e32 vcc, v1, v0
	s_nop 1
	v_cndmask_b32_e32 v2, v2, v4, vcc
	v_mad_u64_u32 v[0:1], s[4:5], v0, v2, v[0:1]
	v_mov_b32_e32 v4, v0
	v_cmp_ne_u32_e32 vcc, v3, v0
	v_mov_b64_e32 v[0:1], s[0:1]
	s_and_saveexec_b64 s[4:5], vcc
	s_cbranch_execz .LBB0_106
	v_mov_b64_e32 v[0:1], s[98:99]
	flat_load_dword v0, v[0:1] sc1
	s_mov_b64 s[10:11], 0
	s_waitcnt vmcnt(0) lgkmcnt(0)
	v_cmp_lt_u32_e32 vcc, v0, v4
	s_and_saveexec_b64 s[8:9], vcc
	s_cbranch_execz .LBB0_105
	s_add_u32 s6, s38, 0x200
	s_addc_u32 s7, s39, 0
	s_mov_b32 s22, 1
	s_branch .LBB0_98

.LBB0_103:
	v_mov_b64_e32 v[0:1], s[98:99]
	flat_load_dword v0, v[0:1] sc1
	s_add_i32 s22, s22, 1
	s_or_b64 s[14:15], s[14:15], exec
	s_waitcnt vmcnt(0) lgkmcnt(0)
	v_cmp_ge_u32_e32 vcc, v0, v4
	s_orn2_b64 s[18:19], vcc, exec
	s_branch .LBB0_97

.LBB0_263:
	s_andn2_saveexec_b64 s[0:1], s[0:1]
	s_cbranch_execz .LBB0_279
	v_mov_b32_e32 v1, s36
	v_add_co_u32_e32 v2, vcc, 0x3000, v1
	v_mov_b32_e32 v1, s37
	buffer_wbl2 sc1
	s_waitcnt vmcnt(0)
	buffer_inv sc1
	v_addc_co_u32_e32 v3, vcc, 0, v1, vcc
	v_mov_b32_e32 v1, 1
	flat_atomic_add v1, v[2:3], v1 offset:1024 sc0
	v_cvt_f32_u32_e32 v2, v0
	v_sub_u32_e32 v3, 0, v0
	s_mov_b64 s[4:5], 0
	v_rcp_iflag_f32_e32 v2, v2
	s_nop 0
	v_mul_f32_e32 v2, 0x4f7ffffe, v2
	v_cvt_u32_f32_e32 v2, v2
	v_mul_lo_u32 v3, v3, v2
	v_mul_hi_u32 v3, v2, v3
	v_add_u32_e32 v2, v2, v3
	s_waitcnt vmcnt(0) lgkmcnt(0)
	v_mul_hi_u32 v2, v1, v2
	v_mul_lo_u32 v3, v2, v0
	v_sub_u32_e32 v3, v1, v3
	v_cmp_ge_u32_e32 vcc, v3, v0
	v_add_u32_e32 v4, 1, v2
	s_nop 0
	v_cndmask_b32_e32 v2, v2, v4, vcc
	v_sub_u32_e32 v4, v3, v0
	v_cndmask_b32_e32 v3, v3, v4, vcc
	v_cmp_ge_u32_e32 vcc, v3, v0
	v_add_u32_e32 v3, 1, v2
	s_nop 0
	v_cndmask_b32_e32 v2, v2, v3, vcc
	v_add_u32_e32 v3, 1, v1
	v_mad_u64_u32 v[0:1], s[0:1], v0, v2, v[0:1]
	v_mov_b32_e32 v4, v0
	s_add_u32 s0, s36, 0x3500
	s_addc_u32 s1, s37, 0
	s_add_u32 s98, s36, 0x3400
	s_addc_u32 s99, s37, 0
	v_cmp_ne_u32_e32 vcc, v3, v0
	v_mov_b64_e32 v[0:1], s[0:1]
	s_and_saveexec_b64 s[2:3], vcc
	s_cbranch_execz .LBB0_276
	v_mov_b64_e32 v[0:1], s[98:99]
	flat_load_dword v0, v[0:1] sc1
	s_mov_b64 s[8:9], 0
	s_waitcnt vmcnt(0) lgkmcnt(0)
	v_cmp_lt_u32_e32 vcc, v0, v4
	s_and_saveexec_b64 s[6:7], vcc
	s_cbranch_execz .LBB0_275
	s_add_u32 s4, s36, 0x200
	s_addc_u32 s5, s37, 0
	s_mov_b32 s21, 1
	s_branch .LBB0_268

.LBB0_273:
	v_mov_b64_e32 v[0:1], s[98:99]
	flat_load_dword v0, v[0:1] sc1
	s_add_i32 s21, s21, 1
	s_or_b64 s[12:13], s[12:13], exec
	s_waitcnt vmcnt(0) lgkmcnt(0)
	v_cmp_ge_u32_e32 vcc, v0, v4
	s_orn2_b64 s[16:17], vcc, exec
	s_branch .LBB0_267

.LBB0_1050:
	s_andn2_saveexec_b64 s[0:1], s[0:1]
	s_cbranch_execz .LBB0_1066
	v_mov_b32_e32 v1, s34
	v_add_co_u32_e32 v2, vcc, 0x3000, v1
	v_mov_b32_e32 v1, s35
	buffer_wbl2 sc1
	s_waitcnt vmcnt(0)
	buffer_inv sc1
	v_addc_co_u32_e32 v3, vcc, 0, v1, vcc
	v_mov_b32_e32 v1, 1
	flat_atomic_add v1, v[2:3], v1 offset:1024 sc0
	v_cvt_f32_u32_e32 v2, v0
	v_sub_u32_e32 v3, 0, v0
	s_mov_b64 s[4:5], 0
	v_rcp_iflag_f32_e32 v2, v2
	s_nop 0
	v_mul_f32_e32 v2, 0x4f7ffffe, v2
	v_cvt_u32_f32_e32 v2, v2
	v_mul_lo_u32 v3, v3, v2
	v_mul_hi_u32 v3, v2, v3
	v_add_u32_e32 v2, v2, v3
	s_waitcnt vmcnt(0) lgkmcnt(0)
	v_mul_hi_u32 v2, v1, v2
	v_mul_lo_u32 v3, v2, v0
	v_sub_u32_e32 v3, v1, v3
	v_cmp_ge_u32_e32 vcc, v3, v0
	v_add_u32_e32 v4, 1, v2
	s_nop 0
	v_cndmask_b32_e32 v2, v2, v4, vcc
	v_sub_u32_e32 v4, v3, v0
	v_cndmask_b32_e32 v3, v3, v4, vcc
	v_cmp_ge_u32_e32 vcc, v3, v0
	v_add_u32_e32 v3, 1, v2
	s_nop 0
	v_cndmask_b32_e32 v2, v2, v3, vcc
	v_add_u32_e32 v3, 1, v1
	v_mad_u64_u32 v[0:1], s[0:1], v0, v2, v[0:1]
	v_mov_b32_e32 v4, v0
	s_add_u32 s0, s34, 0x3500
	s_addc_u32 s1, s35, 0
	s_add_u32 s98, s34, 0x3400
	s_addc_u32 s99, s35, 0
	v_cmp_ne_u32_e32 vcc, v3, v0
	v_mov_b64_e32 v[0:1], s[0:1]
	s_and_saveexec_b64 s[2:3], vcc
	s_cbranch_execz .LBB0_1063
	v_mov_b64_e32 v[0:1], s[98:99]
	flat_load_dword v0, v[0:1] sc1
	s_mov_b64 s[8:9], 0
	s_waitcnt vmcnt(0) lgkmcnt(0)
	v_cmp_lt_u32_e32 vcc, v0, v4
	s_and_saveexec_b64 s[6:7], vcc
	s_cbranch_execz .LBB0_1062
	s_add_u32 s4, s34, 0x200
	s_addc_u32 s5, s35, 0
	s_mov_b32 s21, 1
	s_branch .LBB0_1055

.LBB0_1299:
	s_andn2_saveexec_b64 s[0:1], s[0:1]
	s_cbranch_execz .LBB0_1315
	v_mov_b32_e32 v1, s34
	v_add_co_u32_e32 v2, vcc, 0x3000, v1
	v_mov_b32_e32 v1, s35
	buffer_wbl2 sc1
	s_waitcnt vmcnt(0)
	buffer_inv sc1
	v_addc_co_u32_e32 v3, vcc, 0, v1, vcc
	v_mov_b32_e32 v1, 1
	flat_atomic_add v1, v[2:3], v1 offset:1024 sc0
	v_cvt_f32_u32_e32 v2, v0
	v_sub_u32_e32 v3, 0, v0
	s_add_u32 s0, s34, 0x3500
	s_addc_u32 s1, s35, 0
	s_add_u32 s98, s34, 0x3400
	s_addc_u32 s99, s35, 0
	v_rcp_iflag_f32_e32 v2, v2
	s_mov_b64 s[4:5], 0
	v_mul_f32_e32 v2, 0x4f7ffffe, v2
	v_cvt_u32_f32_e32 v2, v2
	v_mul_lo_u32 v3, v3, v2
	v_mul_hi_u32 v3, v2, v3
	v_add_u32_e32 v2, v2, v3
	s_waitcnt vmcnt(0) lgkmcnt(0)
	v_mul_hi_u32 v2, v1, v2
	v_mul_lo_u32 v4, v2, v0
	v_add_u32_e32 v3, 1, v1
	v_sub_u32_e32 v1, v1, v4
	v_add_u32_e32 v5, 1, v2
	v_cmp_ge_u32_e32 vcc, v1, v0
	v_sub_u32_e32 v4, v1, v0
	s_nop 0
	v_cndmask_b32_e32 v2, v2, v5, vcc
	v_cndmask_b32_e32 v1, v1, v4, vcc
	v_add_u32_e32 v4, 1, v2
	v_cmp_ge_u32_e32 vcc, v1, v0
	s_nop 1
	v_cndmask_b32_e32 v2, v2, v4, vcc
	v_mad_u64_u32 v[0:1], s[2:3], v0, v2, v[0:1]
	v_mov_b32_e32 v4, v0
	v_cmp_ne_u32_e32 vcc, v3, v0
	v_mov_b64_e32 v[0:1], s[0:1]
	s_and_saveexec_b64 s[2:3], vcc
	s_cbranch_execz .LBB0_1312
	v_mov_b64_e32 v[0:1], s[98:99]
	flat_load_dword v0, v[0:1] sc1
	s_mov_b64 s[8:9], 0
	s_waitcnt vmcnt(0) lgkmcnt(0)
	v_cmp_lt_u32_e32 vcc, v0, v4
	s_and_saveexec_b64 s[6:7], vcc
	s_cbranch_execz .LBB0_1311
	s_add_u32 s4, s34, 0x200
	s_addc_u32 s5, s35, 0
	s_mov_b32 s21, 1
	s_branch .LBB0_1304

.LBB0_1572:
	s_andn2_saveexec_b64 s[0:1], s[0:1]
	s_cbranch_execz .LBB0_1588
	v_mov_b32_e32 v1, s38
	v_add_co_u32_e32 v2, vcc, 0x3000, v1
	v_mov_b32_e32 v1, s39
	buffer_wbl2 sc1
	s_waitcnt vmcnt(0)
	buffer_inv sc1
	v_addc_co_u32_e32 v3, vcc, 0, v1, vcc
	v_mov_b32_e32 v1, 1
	flat_atomic_add v1, v[2:3], v1 offset:1024 sc0
	v_cvt_f32_u32_e32 v2, v0
	v_sub_u32_e32 v3, 0, v0
	s_add_u32 s0, s38, 0x3500
	s_addc_u32 s1, s39, 0
	s_add_u32 s98, s38, 0x3400
	s_addc_u32 s99, s39, 0
	v_rcp_iflag_f32_e32 v2, v2
	s_mov_b64 s[4:5], 0
	v_mul_f32_e32 v2, 0x4f7ffffe, v2
	v_cvt_u32_f32_e32 v2, v2
	v_mul_lo_u32 v3, v3, v2
	v_mul_hi_u32 v3, v2, v3
	v_add_u32_e32 v2, v2, v3
	s_waitcnt vmcnt(0) lgkmcnt(0)
	v_mul_hi_u32 v2, v1, v2
	v_mul_lo_u32 v4, v2, v0
	v_add_u32_e32 v3, 1, v1
	v_sub_u32_e32 v1, v1, v4
	v_add_u32_e32 v5, 1, v2
	v_cmp_ge_u32_e32 vcc, v1, v0
	v_sub_u32_e32 v4, v1, v0
	s_nop 0
	v_cndmask_b32_e32 v2, v2, v5, vcc
	v_cndmask_b32_e32 v1, v1, v4, vcc
	v_add_u32_e32 v4, 1, v2
	v_cmp_ge_u32_e32 vcc, v1, v0
	s_nop 1
	v_cndmask_b32_e32 v2, v2, v4, vcc
	v_mad_u64_u32 v[0:1], s[2:3], v0, v2, v[0:1]
	v_mov_b32_e32 v4, v0
	v_cmp_ne_u32_e32 vcc, v3, v0
	v_mov_b64_e32 v[0:1], s[0:1]
	s_and_saveexec_b64 s[2:3], vcc
	s_cbranch_execz .LBB0_1585
	v_mov_b64_e32 v[0:1], s[98:99]
	flat_load_dword v0, v[0:1] sc1
	s_mov_b64 s[8:9], 0
	s_waitcnt vmcnt(0) lgkmcnt(0)
	v_cmp_lt_u32_e32 vcc, v0, v4
	s_and_saveexec_b64 s[6:7], vcc
	s_cbranch_execz .LBB0_1584
	s_add_u32 s4, s38, 0x200
	s_addc_u32 s5, s39, 0
	s_mov_b32 s21, 1
	s_branch .LBB0_1577

.LBB0_1692:
	s_andn2_saveexec_b64 s[0:1], s[0:1]
	s_cbranch_execz .LBB0_1708
	v_mov_b32_e32 v1, s40
	v_add_co_u32_e32 v2, vcc, 0x3000, v1
	v_mov_b32_e32 v1, s41
	buffer_wbl2 sc1
	s_waitcnt vmcnt(0)
	buffer_inv sc1
	v_addc_co_u32_e32 v3, vcc, 0, v1, vcc
	v_mov_b32_e32 v1, 1
	flat_atomic_add v1, v[2:3], v1 offset:1024 sc0
	v_cvt_f32_u32_e32 v2, v0
	v_sub_u32_e32 v3, 0, v0
	s_add_u32 s0, s40, 0x3500
	s_addc_u32 s1, s41, 0
	s_add_u32 s98, s40, 0x3400
	s_addc_u32 s99, s41, 0
	v_rcp_iflag_f32_e32 v2, v2
	s_mov_b64 s[4:5], 0
	v_mul_f32_e32 v2, 0x4f7ffffe, v2
	v_cvt_u32_f32_e32 v2, v2
	v_mul_lo_u32 v3, v3, v2
	v_mul_hi_u32 v3, v2, v3
	v_add_u32_e32 v2, v2, v3
	s_waitcnt vmcnt(0) lgkmcnt(0)
	v_mul_hi_u32 v2, v1, v2
	v_mul_lo_u32 v4, v2, v0
	v_add_u32_e32 v3, 1, v1
	v_sub_u32_e32 v1, v1, v4
	v_add_u32_e32 v5, 1, v2
	v_cmp_ge_u32_e32 vcc, v1, v0
	v_sub_u32_e32 v4, v1, v0
	s_nop 0
	v_cndmask_b32_e32 v2, v2, v5, vcc
	v_cndmask_b32_e32 v1, v1, v4, vcc
	v_add_u32_e32 v4, 1, v2
	v_cmp_ge_u32_e32 vcc, v1, v0
	s_nop 1
	v_cndmask_b32_e32 v2, v2, v4, vcc
	v_mad_u64_u32 v[0:1], s[2:3], v0, v2, v[0:1]
	v_mov_b32_e32 v4, v0
	v_cmp_ne_u32_e32 vcc, v3, v0
	v_mov_b64_e32 v[0:1], s[0:1]
	s_and_saveexec_b64 s[2:3], vcc
	s_cbranch_execz .LBB0_1705
	v_mov_b64_e32 v[0:1], s[98:99]
	flat_load_dword v0, v[0:1] sc1
	s_mov_b64 s[8:9], 0
	s_waitcnt vmcnt(0) lgkmcnt(0)
	v_cmp_lt_u32_e32 vcc, v0, v4
	s_and_saveexec_b64 s[6:7], vcc
	s_cbranch_execz .LBB0_1704
	s_add_u32 s4, s40, 0x200
	s_addc_u32 s5, s41, 0
	s_mov_b32 s21, 1
	s_branch .LBB0_1697

.LBB0_1742:
	s_andn2_saveexec_b64 s[0:1], s[0:1]
	s_cbranch_execz .LBB0_1758
	v_mov_b32_e32 v1, s42
	v_add_co_u32_e32 v2, vcc, 0x3000, v1
	v_mov_b32_e32 v1, s43
	buffer_wbl2 sc1
	s_waitcnt vmcnt(0)
	buffer_inv sc1
	v_addc_co_u32_e32 v3, vcc, 0, v1, vcc
	v_mov_b32_e32 v1, 1
	flat_atomic_add v1, v[2:3], v1 offset:1024 sc0
	v_cvt_f32_u32_e32 v2, v0
	v_sub_u32_e32 v3, 0, v0
	s_add_u32 s0, s42, 0x3500
	s_addc_u32 s1, s43, 0
	s_add_u32 s98, s42, 0x3400
	s_addc_u32 s99, s43, 0
	v_rcp_iflag_f32_e32 v2, v2
	s_mov_b64 s[4:5], 0
	v_mul_f32_e32 v2, 0x4f7ffffe, v2
	v_cvt_u32_f32_e32 v2, v2
	v_mul_lo_u32 v3, v3, v2
	v_mul_hi_u32 v3, v2, v3
	v_add_u32_e32 v2, v2, v3
	s_waitcnt vmcnt(0) lgkmcnt(0)
	v_mul_hi_u32 v2, v1, v2
	v_mul_lo_u32 v4, v2, v0
	v_add_u32_e32 v3, 1, v1
	v_sub_u32_e32 v1, v1, v4
	v_add_u32_e32 v5, 1, v2
	v_cmp_ge_u32_e32 vcc, v1, v0
	v_sub_u32_e32 v4, v1, v0
	s_nop 0
	v_cndmask_b32_e32 v2, v2, v5, vcc
	v_cndmask_b32_e32 v1, v1, v4, vcc
	v_add_u32_e32 v4, 1, v2
	v_cmp_ge_u32_e32 vcc, v1, v0
	s_nop 1
	v_cndmask_b32_e32 v2, v2, v4, vcc
	v_mad_u64_u32 v[0:1], s[2:3], v0, v2, v[0:1]
	v_mov_b32_e32 v4, v0
	v_cmp_ne_u32_e32 vcc, v3, v0
	v_mov_b64_e32 v[0:1], s[0:1]
	s_and_saveexec_b64 s[2:3], vcc
	s_cbranch_execz .LBB0_1755
	v_mov_b64_e32 v[0:1], s[98:99]
	flat_load_dword v0, v[0:1] sc1
	s_mov_b64 s[10:11], 0
	s_waitcnt vmcnt(0) lgkmcnt(0)
	v_cmp_lt_u32_e32 vcc, v0, v4
	s_and_saveexec_b64 s[8:9], vcc
	s_cbranch_execz .LBB0_1754
	s_add_u32 s4, s42, 0x200
	s_addc_u32 s5, s43, 0
	s_mov_b32 s23, 1
	s_branch .LBB0_1747

.LBB0_1752:
	v_mov_b64_e32 v[0:1], s[98:99]
	flat_load_dword v0, v[0:1] sc1
	s_add_i32 s23, s23, 1
	s_or_b64 s[14:15], s[14:15], exec
	s_waitcnt vmcnt(0) lgkmcnt(0)
	v_cmp_ge_u32_e32 vcc, v0, v4
	s_orn2_b64 s[18:19], vcc, exec
	s_branch .LBB0_1746

.LBB0_1814:
	s_andn2_saveexec_b64 s[0:1], s[0:1]
	s_cbranch_execz .LBB0_1830
	v_mov_b32_e32 v1, s40
	v_add_co_u32_e32 v2, vcc, 0x3000, v1
	v_mov_b32_e32 v1, s41
	buffer_wbl2 sc1
	s_waitcnt vmcnt(0)
	buffer_inv sc1
	v_addc_co_u32_e32 v3, vcc, 0, v1, vcc
	v_mov_b32_e32 v1, 1
	flat_atomic_add v1, v[2:3], v1 offset:1024 sc0
	v_cvt_f32_u32_e32 v2, v0
	v_sub_u32_e32 v3, 0, v0
	s_add_u32 s0, s40, 0x3500
	s_addc_u32 s1, s41, 0
	s_add_u32 s98, s40, 0x3400
	s_addc_u32 s99, s41, 0
	v_rcp_iflag_f32_e32 v2, v2
	s_mov_b64 s[4:5], 0
	v_mul_f32_e32 v2, 0x4f7ffffe, v2
	v_cvt_u32_f32_e32 v2, v2
	v_mul_lo_u32 v3, v3, v2
	v_mul_hi_u32 v3, v2, v3
	v_add_u32_e32 v2, v2, v3
	s_waitcnt vmcnt(0) lgkmcnt(0)
	v_mul_hi_u32 v2, v1, v2
	v_mul_lo_u32 v4, v2, v0
	v_add_u32_e32 v3, 1, v1
	v_sub_u32_e32 v1, v1, v4
	v_add_u32_e32 v5, 1, v2
	v_cmp_ge_u32_e32 vcc, v1, v0
	v_sub_u32_e32 v4, v1, v0
	s_nop 0
	v_cndmask_b32_e32 v2, v2, v5, vcc
	v_cndmask_b32_e32 v1, v1, v4, vcc
	v_add_u32_e32 v4, 1, v2
	v_cmp_ge_u32_e32 vcc, v1, v0
	s_nop 1
	v_cndmask_b32_e32 v2, v2, v4, vcc
	v_mad_u64_u32 v[0:1], s[2:3], v0, v2, v[0:1]
	v_mov_b32_e32 v4, v0
	v_cmp_ne_u32_e32 vcc, v3, v0
	v_mov_b64_e32 v[0:1], s[0:1]
	s_and_saveexec_b64 s[2:3], vcc
	s_cbranch_execz .LBB0_1827
	v_mov_b64_e32 v[0:1], s[98:99]
	flat_load_dword v0, v[0:1] sc1
	s_mov_b64 s[10:11], 0
	s_waitcnt vmcnt(0) lgkmcnt(0)
	v_cmp_lt_u32_e32 vcc, v0, v4
	s_and_saveexec_b64 s[8:9], vcc
	s_cbranch_execz .LBB0_1826
	s_add_u32 s4, s40, 0x200
	s_addc_u32 s5, s41, 0
	s_mov_b32 s23, 1
	s_branch .LBB0_1819

.LBB0_1934:
	s_andn2_saveexec_b64 s[0:1], s[0:1]
	s_cbranch_execz .LBB0_1950
	v_mov_b32_e32 v1, s76
	v_add_co_u32_e32 v2, vcc, 0x3000, v1
	v_mov_b32_e32 v1, s77
	buffer_wbl2 sc1
	s_waitcnt vmcnt(0)
	buffer_inv sc1
	v_addc_co_u32_e32 v3, vcc, 0, v1, vcc
	v_mov_b32_e32 v1, 1
	flat_atomic_add v1, v[2:3], v1 offset:1024 sc0
	v_cvt_f32_u32_e32 v2, v0
	v_sub_u32_e32 v3, 0, v0
	s_add_u32 s0, s76, 0x3500
	s_addc_u32 s1, s77, 0
	s_add_u32 s98, s76, 0x3400
	s_addc_u32 s99, s77, 0
	v_rcp_iflag_f32_e32 v2, v2
	s_mov_b64 s[4:5], 0
	v_mul_f32_e32 v2, 0x4f7ffffe, v2
	v_cvt_u32_f32_e32 v2, v2
	v_mul_lo_u32 v3, v3, v2
	v_mul_hi_u32 v3, v2, v3
	v_add_u32_e32 v2, v2, v3
	s_waitcnt vmcnt(0) lgkmcnt(0)
	v_mul_hi_u32 v2, v1, v2
	v_mul_lo_u32 v4, v2, v0
	v_add_u32_e32 v3, 1, v1
	v_sub_u32_e32 v1, v1, v4
	v_add_u32_e32 v5, 1, v2
	v_cmp_ge_u32_e32 vcc, v1, v0
	v_sub_u32_e32 v4, v1, v0
	s_nop 0
	v_cndmask_b32_e32 v2, v2, v5, vcc
	v_cndmask_b32_e32 v1, v1, v4, vcc
	v_add_u32_e32 v4, 1, v2
	v_cmp_ge_u32_e32 vcc, v1, v0
	s_nop 1
	v_cndmask_b32_e32 v2, v2, v4, vcc
	v_mad_u64_u32 v[0:1], s[2:3], v0, v2, v[0:1]
	v_mov_b32_e32 v4, v0
	v_cmp_ne_u32_e32 vcc, v3, v0
	v_mov_b64_e32 v[0:1], s[0:1]
	s_and_saveexec_b64 s[2:3], vcc
	s_cbranch_execz .LBB0_1947
	v_mov_b64_e32 v[0:1], s[98:99]
	flat_load_dword v0, v[0:1] sc1
	s_mov_b64 s[10:11], 0
	s_waitcnt vmcnt(0) lgkmcnt(0)
	v_cmp_lt_u32_e32 vcc, v0, v4
	s_and_saveexec_b64 s[8:9], vcc
	s_cbranch_execz .LBB0_1946
	s_add_u32 s4, s76, 0x200
	s_addc_u32 s5, s77, 0
	s_mov_b32 s23, 1
	s_branch .LBB0_1939
